# instruction selection: GEMM1 gate-tile epilogue's 128 in-place -log2e multiplies become 64 v_pk_mul_f32 (constant in a dead fragment register)
# speedup vs baseline: 1.0035x; 1.0035x over previous
; __device__ __forceinline__ float sigmoidf_fast(float x) { return __builtin_amdgcn_rcpf(1.0f + __builtin_amdgcn_exp2f(-1.4426950408889634f * x)); }
;     __device__ __forceinline__ void operator()(const f32x4 (&acc)[2][2][4][2], const Unit& u, int wr, int wc, int fr, int fq) const {
;     ...
;         if (u.pn >= 30) {
;             const int tidn = (wr * 4 + wc) * 64 + fq * 16 + fr;
;             u32x4* gp = (u32x4*)G8 + (size_t)(u.pm * 16 + (u.pn - 30)) * 8 * 512 + tidn;
; #pragma unroll
;             for (int ai = 0; ai < 2; ++ai)
; #pragma unroll
;                 for (int m = 0; m < 4; ++m) { unsigned q[16];
; #pragma unroll
;                     for (int bj = 0; bj < 2; ++bj) { const f32x4 v0 = acc[ai][bj][m][0], v1 = acc[ai][bj][m][1];
; #pragma unroll
;                         for (int e = 0; e < 4; ++e) { q[8 * bj + e] = (unsigned)fmaf(sigmoidf_fast(v0[e]), 255.0f, 0.5f); q[8 * bj + 4 + e] = (unsigned)fmaf(sigmoidf_fast(v1[e]), 255.0f, 0.5f); } }
;                     u32x4 w; w.x = q[0] | (q[1] << 8) | (q[2] << 16) | (q[3] << 24); w.y = q[4] | (q[5] << 8) | (q[6] << 16) | (q[7] << 24);
;                     w.z = q[8] | (q[9] << 8) | (q[10] << 16) | (q[11] << 24); w.w = q[12] | (q[13] << 8) | (q[14] << 16) | (q[15] << 24);
;                     gp[(ai * 4 + m) * 512] = w; }
.LBB0_288:
	v_mov_b32_e32 v204, 0xbfb8aa3b
	v_pk_mul_f32 v[126:127], v[126:127], v[204:205] op_sel_hi:[1,0]
	v_pk_mul_f32 v[122:123], v[122:123], v[204:205] op_sel_hi:[1,0]
	v_exp_f32_e32 v126, v126
	v_exp_f32_e32 v158, v122
	v_add_f32_e32 v122, 1.0, v126
	v_add_f32_e32 v126, 1.0, v158
	v_exp_f32_e32 v127, v127
	v_exp_f32_e32 v158, v123
	v_pk_mul_f32 v[128:129], v[128:129], v[204:205] op_sel_hi:[1,0]
	v_pk_mul_f32 v[124:125], v[124:125], v[204:205] op_sel_hi:[1,0]
	v_rcp_f32_e32 v123, v126
	v_add_f32_e32 v126, 1.0, v127
	v_add_f32_e32 v127, 1.0, v158
	v_exp_f32_e32 v128, v128
	v_exp_f32_e32 v158, v124
	v_add_f32_e32 v124, 1.0, v128
	v_add_f32_e32 v128, 1.0, v158
	v_exp_f32_e32 v129, v129
	v_exp_f32_e32 v158, v125
	v_pk_mul_f32 v[118:119], v[118:119], v[204:205] op_sel_hi:[1,0]
	v_pk_mul_f32 v[114:115], v[114:115], v[204:205] op_sel_hi:[1,0]
	v_rcp_f32_e32 v125, v128
	v_add_f32_e32 v128, 1.0, v129
	v_add_f32_e32 v129, 1.0, v158
	v_exp_f32_e32 v118, v118
	v_exp_f32_e32 v158, v114
	v_add_f32_e32 v114, 1.0, v118
	v_add_f32_e32 v118, 1.0, v158
	v_exp_f32_e32 v119, v119
	v_exp_f32_e32 v158, v115
	v_pk_mul_f32 v[120:121], v[120:121], v[204:205] op_sel_hi:[1,0]
	v_pk_mul_f32 v[116:117], v[116:117], v[204:205] op_sel_hi:[1,0]
	v_rcp_f32_e32 v115, v118
	v_add_f32_e32 v118, 1.0, v119
	v_add_f32_e32 v119, 1.0, v158
	v_exp_f32_e32 v120, v120
	v_exp_f32_e32 v158, v116
	v_rcp_f32_e32 v114, v114
	v_rcp_f32_e32 v118, v118
	v_rcp_f32_e32 v119, v119
	v_rcp_f32_e32 v122, v122
	v_rcp_f32_e32 v126, v126
	v_rcp_f32_e32 v127, v127
	v_add_f32_e32 v116, 1.0, v120
	v_add_f32_e32 v120, 1.0, v158
	v_exp_f32_e32 v121, v121
	v_exp_f32_e32 v158, v117
	v_pk_fma_f32 v[118:119], v[118:119], s[16:17], 0.5 op_sel_hi:[1,0,0]
	v_pk_fma_f32 v[114:115], v[114:115], s[16:17], 0.5 op_sel_hi:[1,0,0]
	v_rcp_f32_e32 v124, v124
	v_rcp_f32_e32 v116, v116
	v_rcp_f32_e32 v117, v120
	v_add_f32_e32 v120, 1.0, v121
	v_add_f32_e32 v121, 1.0, v158
	v_pk_fma_f32 v[126:127], v[126:127], s[16:17], 0.5 op_sel_hi:[1,0,0]
	v_cvt_u32_f32_e32 v158, v119
	v_cvt_u32_f32_e32 v159, v118
	v_pk_fma_f32 v[118:119], v[122:123], s[16:17], 0.5 op_sel_hi:[1,0,0]
	v_cvt_u32_f32_e32 v114, v114
	v_cvt_u32_f32_e32 v115, v115
	v_rcp_f32_e32 v128, v128
	v_rcp_f32_e32 v129, v129
	v_rcp_f32_e32 v120, v120
	v_rcp_f32_e32 v121, v121
	v_cvt_u32_f32_e32 v127, v127
	v_cvt_u32_f32_e32 v126, v126
	v_cvt_u32_f32_e32 v118, v118
	v_cvt_u32_f32_e32 v119, v119
	v_lshl_or_b32 v122, v159, 8, v114
	v_lshl_or_b32 v123, v158, 8, v115
	v_pk_fma_f32 v[114:115], v[124:125], s[16:17], 0.5 op_sel_hi:[1,0,0]
	v_pk_fma_f32 v[116:117], v[116:117], s[16:17], 0.5 op_sel_hi:[1,0,0]
	s_lshl_b32 s7, s58, 4
	v_lshl_or_b32 v118, v126, 8, v118
	v_lshl_or_b32 v119, v127, 8, v119
	v_cvt_u32_f32_sdwa v124, v117 dst_sel:WORD_1 dst_unused:UNUSED_PAD src0_sel:DWORD
	v_cvt_u32_f32_sdwa v125, v116 dst_sel:WORD_1 dst_unused:UNUSED_PAD src0_sel:DWORD
	v_cvt_u32_f32_sdwa v126, v115 dst_sel:WORD_1 dst_unused:UNUSED_PAD src0_sel:DWORD
	v_cvt_u32_f32_sdwa v127, v114 dst_sel:WORD_1 dst_unused:UNUSED_PAD src0_sel:DWORD
	v_pk_fma_f32 v[114:115], v[128:129], s[16:17], 0.5 op_sel_hi:[1,0,0]
	v_pk_fma_f32 v[116:117], v[120:121], s[16:17], 0.5 op_sel_hi:[1,0,0]
	s_add_i32 s7, s57, s7
	v_cvt_u32_f32_sdwa v117, v117 dst_sel:BYTE_3 dst_unused:UNUSED_PAD src0_sel:DWORD
	v_cvt_u32_f32_sdwa v116, v116 dst_sel:BYTE_3 dst_unused:UNUSED_PAD src0_sel:DWORD
	v_cvt_u32_f32_sdwa v115, v115 dst_sel:BYTE_3 dst_unused:UNUSED_PAD src0_sel:DWORD
	v_cvt_u32_f32_sdwa v114, v114 dst_sel:BYTE_3 dst_unused:UNUSED_PAD src0_sel:DWORD
	s_sub_i32 s18, s7, 30
	s_ashr_i32 s19, s18, 31
	s_lshl_b64 s[18:19], s[18:19], 16
	v_pk_mul_f32 v[110:111], v[110:111], v[204:205] op_sel_hi:[1,0]
	v_pk_mul_f32 v[106:107], v[106:107], v[204:205] op_sel_hi:[1,0]
	v_lshl_add_u64 v[156:157], v[150:151], 0, s[18:19]
	v_or3_b32 v117, v123, v124, v117
	v_or3_b32 v116, v122, v125, v116
	v_or3_b32 v115, v119, v126, v115
	v_or3_b32 v114, v118, v127, v114
	v_exp_f32_e32 v110, v110
	v_exp_f32_e32 v118, v106
	global_store_dwordx4 v[156:157], v[114:117], off
	v_exp_f32_e32 v111, v111
	v_add_f32_e32 v106, 1.0, v110
	v_exp_f32_e32 v114, v107
	v_add_f32_e32 v110, 1.0, v118
	v_pk_mul_f32 v[112:113], v[112:113], v[204:205] op_sel_hi:[1,0]
	v_pk_mul_f32 v[108:109], v[108:109], v[204:205] op_sel_hi:[1,0]
	v_rcp_f32_e32 v107, v110
	v_add_f32_e32 v110, 1.0, v111
	v_add_f32_e32 v111, 1.0, v114
	v_exp_f32_e32 v112, v112
	v_exp_f32_e32 v114, v108
	v_add_f32_e32 v108, 1.0, v112
	v_add_f32_e32 v112, 1.0, v114
	v_exp_f32_e32 v113, v113
	v_exp_f32_e32 v114, v109
	v_pk_mul_f32 v[102:103], v[102:103], v[204:205] op_sel_hi:[1,0]
	v_pk_mul_f32 v[98:99], v[98:99], v[204:205] op_sel_hi:[1,0]
	v_rcp_f32_e32 v109, v112
	v_add_f32_e32 v112, 1.0, v113
	v_add_f32_e32 v113, 1.0, v114
	v_exp_f32_e32 v102, v102
	v_exp_f32_e32 v114, v98
	v_add_f32_e32 v98, 1.0, v102
	v_add_f32_e32 v102, 1.0, v114
	v_exp_f32_e32 v103, v103
	v_exp_f32_e32 v114, v99
	v_pk_mul_f32 v[104:105], v[104:105], v[204:205] op_sel_hi:[1,0]
	v_pk_mul_f32 v[100:101], v[100:101], v[204:205] op_sel_hi:[1,0]
	v_rcp_f32_e32 v99, v102
	v_add_f32_e32 v102, 1.0, v103
	v_add_f32_e32 v103, 1.0, v114
	v_exp_f32_e32 v104, v104
	v_exp_f32_e32 v114, v100
	v_rcp_f32_e32 v98, v98
	v_rcp_f32_e32 v102, v102
	v_rcp_f32_e32 v103, v103
	v_rcp_f32_e32 v106, v106
	v_rcp_f32_e32 v110, v110
	v_rcp_f32_e32 v111, v111
	v_add_f32_e32 v100, 1.0, v104
	v_add_f32_e32 v104, 1.0, v114
	v_exp_f32_e32 v105, v105
	v_exp_f32_e32 v114, v101
	v_pk_fma_f32 v[102:103], v[102:103], s[16:17], 0.5 op_sel_hi:[1,0,0]
	v_pk_fma_f32 v[98:99], v[98:99], s[16:17], 0.5 op_sel_hi:[1,0,0]
	v_rcp_f32_e32 v108, v108
	v_rcp_f32_e32 v101, v104
; __device__ __forceinline__ float sigmoidf_fast(float x) { return __builtin_amdgcn_rcpf(1.0f + __builtin_amdgcn_exp2f(-1.4426950408889634f * x)); }
;     __device__ __forceinline__ void operator()(const f32x4 (&acc)[2][2][4][2], const Unit& u, int wr, int wc, int fr, int fq) const {
;     ...
;         if (u.pn >= 30) {
;             const int tidn = (wr * 4 + wc) * 64 + fq * 16 + fr;
;             u32x4* gp = (u32x4*)G8 + (size_t)(u.pm * 16 + (u.pn - 30)) * 8 * 512 + tidn;
; #pragma unroll
;             for (int ai = 0; ai < 2; ++ai)
; #pragma unroll
;                 for (int m = 0; m < 4; ++m) { unsigned q[16];
; #pragma unroll
;                     for (int bj = 0; bj < 2; ++bj) { const f32x4 v0 = acc[ai][bj][m][0], v1 = acc[ai][bj][m][1];
; #pragma unroll
;                         for (int e = 0; e < 4; ++e) { q[8 * bj + e] = (unsigned)fmaf(sigmoidf_fast(v0[e]), 255.0f, 0.5f); q[8 * bj + 4 + e] = (unsigned)fmaf(sigmoidf_fast(v1[e]), 255.0f, 0.5f); } }
;                     u32x4 w; w.x = q[0] | (q[1] << 8) | (q[2] << 16) | (q[3] << 24); w.y = q[4] | (q[5] << 8) | (q[6] << 16) | (q[7] << 24);
;                     w.z = q[8] | (q[9] << 8) | (q[10] << 16) | (q[11] << 24); w.w = q[12] | (q[13] << 8) | (q[14] << 16) | (q[15] << 24);
;                     gp[(ai * 4 + m) * 512] = w; }
	v_add_f32_e32 v104, 1.0, v105
	v_add_f32_e32 v105, 1.0, v114
	v_pk_fma_f32 v[110:111], v[110:111], s[16:17], 0.5 op_sel_hi:[1,0,0]
	v_cvt_u32_f32_e32 v114, v103
	v_cvt_u32_f32_e32 v115, v102
	v_pk_fma_f32 v[102:103], v[106:107], s[16:17], 0.5 op_sel_hi:[1,0,0]
	v_cvt_u32_f32_e32 v98, v98
	v_cvt_u32_f32_e32 v99, v99
	v_rcp_f32_e32 v112, v112
	v_rcp_f32_e32 v113, v113
	v_rcp_f32_e32 v100, v100
	v_cvt_u32_f32_e32 v111, v111
	v_cvt_u32_f32_e32 v110, v110
	v_cvt_u32_f32_e32 v102, v102
	v_cvt_u32_f32_e32 v103, v103
	v_rcp_f32_e32 v104, v104
	v_rcp_f32_e32 v105, v105
	v_lshl_or_b32 v106, v115, 8, v98
	v_lshl_or_b32 v107, v114, 8, v99
	v_pk_fma_f32 v[98:99], v[108:109], s[16:17], 0.5 op_sel_hi:[1,0,0]
	v_lshl_or_b32 v102, v110, 8, v102
	v_lshl_or_b32 v103, v111, 8, v103
	v_pk_fma_f32 v[100:101], v[100:101], s[16:17], 0.5 op_sel_hi:[1,0,0]
	v_cvt_u32_f32_sdwa v110, v99 dst_sel:WORD_1 dst_unused:UNUSED_PAD src0_sel:DWORD
	v_cvt_u32_f32_sdwa v111, v98 dst_sel:WORD_1 dst_unused:UNUSED_PAD src0_sel:DWORD
	v_pk_fma_f32 v[98:99], v[112:113], s[16:17], 0.5 op_sel_hi:[1,0,0]
	v_cvt_u32_f32_sdwa v108, v101 dst_sel:WORD_1 dst_unused:UNUSED_PAD src0_sel:DWORD
	v_cvt_u32_f32_sdwa v109, v100 dst_sel:WORD_1 dst_unused:UNUSED_PAD src0_sel:DWORD
	v_pk_fma_f32 v[100:101], v[104:105], s[16:17], 0.5 op_sel_hi:[1,0,0]
	v_cvt_u32_f32_sdwa v98, v98 dst_sel:BYTE_3 dst_unused:UNUSED_PAD src0_sel:DWORD
	v_cvt_u32_f32_sdwa v101, v101 dst_sel:BYTE_3 dst_unused:UNUSED_PAD src0_sel:DWORD
	v_cvt_u32_f32_sdwa v100, v100 dst_sel:BYTE_3 dst_unused:UNUSED_PAD src0_sel:DWORD
	v_cvt_u32_f32_sdwa v99, v99 dst_sel:BYTE_3 dst_unused:UNUSED_PAD src0_sel:DWORD
	s_movk_i32 s7, 0x2000
	v_or3_b32 v98, v102, v111, v98
	v_add_co_u32_e32 v102, vcc, s7, v156
	v_pk_mul_f32 v[94:95], v[94:95], v[204:205] op_sel_hi:[1,0]
	v_pk_mul_f32 v[90:91], v[90:91], v[204:205] op_sel_hi:[1,0]
	v_or3_b32 v101, v107, v108, v101
	v_or3_b32 v100, v106, v109, v100
	v_or3_b32 v99, v103, v110, v99
	v_addc_co_u32_e32 v103, vcc, 0, v157, vcc
	v_exp_f32_e32 v94, v94
	v_exp_f32_e32 v104, v90
	global_store_dwordx4 v[102:103], v[98:101], off
	v_exp_f32_e32 v95, v95
	v_add_f32_e32 v90, 1.0, v94
	v_exp_f32_e32 v98, v91
	v_add_f32_e32 v94, 1.0, v104
	v_pk_mul_f32 v[96:97], v[96:97], v[204:205] op_sel_hi:[1,0]
	v_pk_mul_f32 v[92:93], v[92:93], v[204:205] op_sel_hi:[1,0]
	v_rcp_f32_e32 v91, v94
	v_add_f32_e32 v94, 1.0, v95
	v_add_f32_e32 v95, 1.0, v98
	v_exp_f32_e32 v96, v96
	v_exp_f32_e32 v98, v92
	v_add_f32_e32 v92, 1.0, v96
	v_add_f32_e32 v96, 1.0, v98
	v_exp_f32_e32 v97, v97
	v_exp_f32_e32 v98, v93
	v_pk_mul_f32 v[86:87], v[86:87], v[204:205] op_sel_hi:[1,0]
	v_pk_mul_f32 v[82:83], v[82:83], v[204:205] op_sel_hi:[1,0]
	v_rcp_f32_e32 v93, v96
	v_add_f32_e32 v96, 1.0, v97
	v_add_f32_e32 v97, 1.0, v98
	v_exp_f32_e32 v86, v86
	v_exp_f32_e32 v98, v82
	v_add_f32_e32 v82, 1.0, v86
	v_add_f32_e32 v86, 1.0, v98
	v_exp_f32_e32 v87, v87
	v_exp_f32_e32 v98, v83
	v_pk_mul_f32 v[88:89], v[88:89], v[204:205] op_sel_hi:[1,0]
	v_pk_mul_f32 v[84:85], v[84:85], v[204:205] op_sel_hi:[1,0]
	v_rcp_f32_e32 v83, v86
	v_add_f32_e32 v86, 1.0, v87
	v_add_f32_e32 v87, 1.0, v98
	v_exp_f32_e32 v88, v88
	v_exp_f32_e32 v98, v84
	v_rcp_f32_e32 v82, v82
	v_rcp_f32_e32 v86, v86
	v_rcp_f32_e32 v87, v87
	v_rcp_f32_e32 v90, v90
	v_rcp_f32_e32 v94, v94
	v_rcp_f32_e32 v95, v95
	v_add_f32_e32 v84, 1.0, v88
	v_add_f32_e32 v88, 1.0, v98
	v_exp_f32_e32 v89, v89
	v_exp_f32_e32 v98, v85
	v_pk_fma_f32 v[86:87], v[86:87], s[16:17], 0.5 op_sel_hi:[1,0,0]
	v_pk_fma_f32 v[82:83], v[82:83], s[16:17], 0.5 op_sel_hi:[1,0,0]
	v_rcp_f32_e32 v92, v92
	v_rcp_f32_e32 v85, v88
	v_add_f32_e32 v88, 1.0, v89
	v_add_f32_e32 v89, 1.0, v98
	v_pk_fma_f32 v[94:95], v[94:95], s[16:17], 0.5 op_sel_hi:[1,0,0]
	v_cvt_u32_f32_e32 v98, v87
	v_cvt_u32_f32_e32 v99, v86
	v_pk_fma_f32 v[86:87], v[90:91], s[16:17], 0.5 op_sel_hi:[1,0,0]
	v_cvt_u32_f32_e32 v82, v82
	v_cvt_u32_f32_e32 v83, v83
	v_rcp_f32_e32 v96, v96
	v_rcp_f32_e32 v97, v97
	v_rcp_f32_e32 v84, v84
	v_cvt_u32_f32_e32 v95, v95
	v_cvt_u32_f32_e32 v94, v94
	v_cvt_u32_f32_e32 v86, v86
	v_cvt_u32_f32_e32 v87, v87
	v_rcp_f32_e32 v88, v88
	v_rcp_f32_e32 v89, v89
	v_lshl_or_b32 v90, v99, 8, v82
	v_lshl_or_b32 v91, v98, 8, v83
	v_pk_fma_f32 v[82:83], v[92:93], s[16:17], 0.5 op_sel_hi:[1,0,0]
	v_lshl_or_b32 v86, v94, 8, v86
	v_lshl_or_b32 v87, v95, 8, v87
	v_pk_fma_f32 v[84:85], v[84:85], s[16:17], 0.5 op_sel_hi:[1,0,0]
	v_cvt_u32_f32_sdwa v94, v83 dst_sel:WORD_1 dst_unused:UNUSED_PAD src0_sel:DWORD
	v_cvt_u32_f32_sdwa v95, v82 dst_sel:WORD_1 dst_unused:UNUSED_PAD src0_sel:DWORD
	v_pk_fma_f32 v[82:83], v[96:97], s[16:17], 0.5 op_sel_hi:[1,0,0]
	v_cvt_u32_f32_sdwa v92, v85 dst_sel:WORD_1 dst_unused:UNUSED_PAD src0_sel:DWORD
	v_cvt_u32_f32_sdwa v93, v84 dst_sel:WORD_1 dst_unused:UNUSED_PAD src0_sel:DWORD
	v_pk_fma_f32 v[84:85], v[88:89], s[16:17], 0.5 op_sel_hi:[1,0,0]
	v_cvt_u32_f32_sdwa v82, v82 dst_sel:BYTE_3 dst_unused:UNUSED_PAD src0_sel:DWORD
	v_cvt_u32_f32_sdwa v85, v85 dst_sel:BYTE_3 dst_unused:UNUSED_PAD src0_sel:DWORD
	v_cvt_u32_f32_sdwa v84, v84 dst_sel:BYTE_3 dst_unused:UNUSED_PAD src0_sel:DWORD
	v_cvt_u32_f32_sdwa v83, v83 dst_sel:BYTE_3 dst_unused:UNUSED_PAD src0_sel:DWORD
	v_or3_b32 v82, v86, v95, v82
	v_add_co_u32_e32 v86, vcc, s81, v156
	v_pk_mul_f32 v[78:79], v[78:79], v[204:205] op_sel_hi:[1,0]
	v_pk_mul_f32 v[74:75], v[74:75], v[204:205] op_sel_hi:[1,0]
	v_or3_b32 v85, v91, v92, v85
	v_or3_b32 v84, v90, v93, v84
	v_or3_b32 v83, v87, v94, v83
	v_addc_co_u32_e32 v87, vcc, 0, v157, vcc
	v_exp_f32_e32 v78, v78
	v_exp_f32_e32 v88, v74
	global_store_dwordx4 v[86:87], v[82:85], off
	v_exp_f32_e32 v79, v79
	v_add_f32_e32 v74, 1.0, v78
; __device__ __forceinline__ float sigmoidf_fast(float x) { return __builtin_amdgcn_rcpf(1.0f + __builtin_amdgcn_exp2f(-1.4426950408889634f * x)); }
;     __device__ __forceinline__ void operator()(const f32x4 (&acc)[2][2][4][2], const Unit& u, int wr, int wc, int fr, int fq) const {
;     ...
;         if (u.pn >= 30) {
;             const int tidn = (wr * 4 + wc) * 64 + fq * 16 + fr;
;             u32x4* gp = (u32x4*)G8 + (size_t)(u.pm * 16 + (u.pn - 30)) * 8 * 512 + tidn;
; #pragma unroll
;             for (int ai = 0; ai < 2; ++ai)
; #pragma unroll
;                 for (int m = 0; m < 4; ++m) { unsigned q[16];
; #pragma unroll
;                     for (int bj = 0; bj < 2; ++bj) { const f32x4 v0 = acc[ai][bj][m][0], v1 = acc[ai][bj][m][1];
; #pragma unroll
;                         for (int e = 0; e < 4; ++e) { q[8 * bj + e] = (unsigned)fmaf(sigmoidf_fast(v0[e]), 255.0f, 0.5f); q[8 * bj + 4 + e] = (unsigned)fmaf(sigmoidf_fast(v1[e]), 255.0f, 0.5f); } }
;                     u32x4 w; w.x = q[0] | (q[1] << 8) | (q[2] << 16) | (q[3] << 24); w.y = q[4] | (q[5] << 8) | (q[6] << 16) | (q[7] << 24);
;                     w.z = q[8] | (q[9] << 8) | (q[10] << 16) | (q[11] << 24); w.w = q[12] | (q[13] << 8) | (q[14] << 16) | (q[15] << 24);
;                     gp[(ai * 4 + m) * 512] = w; }
	v_exp_f32_e32 v82, v75
	v_add_f32_e32 v78, 1.0, v88
	v_pk_mul_f32 v[80:81], v[80:81], v[204:205] op_sel_hi:[1,0]
	v_pk_mul_f32 v[76:77], v[76:77], v[204:205] op_sel_hi:[1,0]
	v_rcp_f32_e32 v75, v78
	v_add_f32_e32 v78, 1.0, v79
	v_add_f32_e32 v79, 1.0, v82
	v_exp_f32_e32 v80, v80
	v_exp_f32_e32 v82, v76
	v_add_f32_e32 v76, 1.0, v80
	v_add_f32_e32 v80, 1.0, v82
	v_exp_f32_e32 v81, v81
	v_exp_f32_e32 v82, v77
	v_pk_mul_f32 v[70:71], v[70:71], v[204:205] op_sel_hi:[1,0]
	v_pk_mul_f32 v[66:67], v[66:67], v[204:205] op_sel_hi:[1,0]
	v_rcp_f32_e32 v77, v80
	v_add_f32_e32 v80, 1.0, v81
	v_add_f32_e32 v81, 1.0, v82
	v_exp_f32_e32 v70, v70
	v_exp_f32_e32 v82, v66
	v_add_f32_e32 v66, 1.0, v70
	v_add_f32_e32 v70, 1.0, v82
	v_exp_f32_e32 v71, v71
	v_exp_f32_e32 v82, v67
	v_pk_mul_f32 v[72:73], v[72:73], v[204:205] op_sel_hi:[1,0]
	v_pk_mul_f32 v[68:69], v[68:69], v[204:205] op_sel_hi:[1,0]
	v_rcp_f32_e32 v67, v70
	v_add_f32_e32 v70, 1.0, v71
	v_add_f32_e32 v71, 1.0, v82
	v_exp_f32_e32 v72, v72
	v_exp_f32_e32 v82, v68
	v_rcp_f32_e32 v66, v66
	v_rcp_f32_e32 v70, v70
	v_rcp_f32_e32 v71, v71
	v_rcp_f32_e32 v74, v74
	v_rcp_f32_e32 v78, v78
	v_rcp_f32_e32 v79, v79
	v_add_f32_e32 v68, 1.0, v72
	v_add_f32_e32 v72, 1.0, v82
	v_exp_f32_e32 v73, v73
	v_exp_f32_e32 v82, v69
	v_pk_fma_f32 v[70:71], v[70:71], s[16:17], 0.5 op_sel_hi:[1,0,0]
	v_pk_fma_f32 v[66:67], v[66:67], s[16:17], 0.5 op_sel_hi:[1,0,0]
	v_rcp_f32_e32 v76, v76
	v_rcp_f32_e32 v69, v72
	v_add_f32_e32 v72, 1.0, v73
	v_add_f32_e32 v73, 1.0, v82
	v_pk_fma_f32 v[78:79], v[78:79], s[16:17], 0.5 op_sel_hi:[1,0,0]
	v_cvt_u32_f32_e32 v82, v71
	v_cvt_u32_f32_e32 v83, v70
	v_pk_fma_f32 v[70:71], v[74:75], s[16:17], 0.5 op_sel_hi:[1,0,0]
	v_cvt_u32_f32_e32 v66, v66
	v_cvt_u32_f32_e32 v67, v67
	v_rcp_f32_e32 v80, v80
	v_rcp_f32_e32 v81, v81
	v_rcp_f32_e32 v68, v68
	v_cvt_u32_f32_e32 v79, v79
	v_cvt_u32_f32_e32 v78, v78
	v_cvt_u32_f32_e32 v70, v70
	v_cvt_u32_f32_e32 v71, v71
	v_rcp_f32_e32 v72, v72
	v_rcp_f32_e32 v73, v73
	v_lshl_or_b32 v74, v83, 8, v66
	v_lshl_or_b32 v75, v82, 8, v67
	v_pk_fma_f32 v[66:67], v[76:77], s[16:17], 0.5 op_sel_hi:[1,0,0]
	v_lshl_or_b32 v70, v78, 8, v70
	v_lshl_or_b32 v71, v79, 8, v71
	v_pk_fma_f32 v[68:69], v[68:69], s[16:17], 0.5 op_sel_hi:[1,0,0]
	v_cvt_u32_f32_sdwa v78, v67 dst_sel:WORD_1 dst_unused:UNUSED_PAD src0_sel:DWORD
	v_cvt_u32_f32_sdwa v79, v66 dst_sel:WORD_1 dst_unused:UNUSED_PAD src0_sel:DWORD
	v_pk_fma_f32 v[66:67], v[80:81], s[16:17], 0.5 op_sel_hi:[1,0,0]
	v_cvt_u32_f32_sdwa v76, v69 dst_sel:WORD_1 dst_unused:UNUSED_PAD src0_sel:DWORD
	v_cvt_u32_f32_sdwa v77, v68 dst_sel:WORD_1 dst_unused:UNUSED_PAD src0_sel:DWORD
	v_pk_fma_f32 v[68:69], v[72:73], s[16:17], 0.5 op_sel_hi:[1,0,0]
	v_cvt_u32_f32_sdwa v66, v66 dst_sel:BYTE_3 dst_unused:UNUSED_PAD src0_sel:DWORD
	v_cvt_u32_f32_sdwa v69, v69 dst_sel:BYTE_3 dst_unused:UNUSED_PAD src0_sel:DWORD
	v_cvt_u32_f32_sdwa v68, v68 dst_sel:BYTE_3 dst_unused:UNUSED_PAD src0_sel:DWORD
	v_cvt_u32_f32_sdwa v67, v67 dst_sel:BYTE_3 dst_unused:UNUSED_PAD src0_sel:DWORD
	s_movk_i32 s7, 0x6000
	v_or3_b32 v66, v70, v79, v66
	v_add_co_u32_e32 v70, vcc, s7, v156
	v_pk_mul_f32 v[62:63], v[62:63], v[204:205] op_sel_hi:[1,0]
	v_pk_mul_f32 v[58:59], v[58:59], v[204:205] op_sel_hi:[1,0]
	v_or3_b32 v69, v75, v76, v69
	v_or3_b32 v68, v74, v77, v68
	v_or3_b32 v67, v71, v78, v67
	v_addc_co_u32_e32 v71, vcc, 0, v157, vcc
	v_exp_f32_e32 v62, v62
	v_exp_f32_e32 v72, v58
	global_store_dwordx4 v[70:71], v[66:69], off
	v_exp_f32_e32 v63, v63
	v_add_f32_e32 v58, 1.0, v62
	v_exp_f32_e32 v66, v59
	v_add_f32_e32 v62, 1.0, v72
	v_pk_mul_f32 v[64:65], v[64:65], v[204:205] op_sel_hi:[1,0]
	v_pk_mul_f32 v[60:61], v[60:61], v[204:205] op_sel_hi:[1,0]
	v_rcp_f32_e32 v59, v62
	v_add_f32_e32 v62, 1.0, v63
	v_add_f32_e32 v63, 1.0, v66
	v_exp_f32_e32 v64, v64
	v_exp_f32_e32 v66, v60
	v_add_f32_e32 v60, 1.0, v64
	v_add_f32_e32 v64, 1.0, v66
	v_exp_f32_e32 v65, v65
	v_exp_f32_e32 v66, v61
	v_pk_mul_f32 v[54:55], v[54:55], v[204:205] op_sel_hi:[1,0]
	v_pk_mul_f32 v[50:51], v[50:51], v[204:205] op_sel_hi:[1,0]
	v_rcp_f32_e32 v61, v64
	v_add_f32_e32 v64, 1.0, v65
	v_add_f32_e32 v65, 1.0, v66
	v_exp_f32_e32 v54, v54
	v_exp_f32_e32 v66, v50
	v_add_f32_e32 v50, 1.0, v54
	v_add_f32_e32 v54, 1.0, v66
	v_exp_f32_e32 v55, v55
	v_exp_f32_e32 v66, v51
	v_pk_mul_f32 v[56:57], v[56:57], v[204:205] op_sel_hi:[1,0]
	v_pk_mul_f32 v[52:53], v[52:53], v[204:205] op_sel_hi:[1,0]
	v_rcp_f32_e32 v51, v54
	v_add_f32_e32 v54, 1.0, v55
	v_add_f32_e32 v55, 1.0, v66
	v_exp_f32_e32 v56, v56
	v_exp_f32_e32 v66, v52
	v_rcp_f32_e32 v50, v50
	v_rcp_f32_e32 v54, v54
	v_rcp_f32_e32 v55, v55
	v_rcp_f32_e32 v58, v58
	v_rcp_f32_e32 v62, v62
	v_rcp_f32_e32 v63, v63
	v_add_f32_e32 v52, 1.0, v56
	v_add_f32_e32 v56, 1.0, v66
	v_exp_f32_e32 v57, v57
	v_exp_f32_e32 v66, v53
	v_pk_fma_f32 v[54:55], v[54:55], s[16:17], 0.5 op_sel_hi:[1,0,0]
	v_pk_fma_f32 v[50:51], v[50:51], s[16:17], 0.5 op_sel_hi:[1,0,0]
	v_rcp_f32_e32 v60, v60
	v_rcp_f32_e32 v53, v56
	v_add_f32_e32 v56, 1.0, v57
	v_add_f32_e32 v57, 1.0, v66
	v_pk_fma_f32 v[62:63], v[62:63], s[16:17], 0.5 op_sel_hi:[1,0,0]
	v_cvt_u32_f32_e32 v66, v55
	v_cvt_u32_f32_e32 v67, v54
	v_pk_fma_f32 v[54:55], v[58:59], s[16:17], 0.5 op_sel_hi:[1,0,0]
	v_cvt_u32_f32_e32 v50, v50
	v_cvt_u32_f32_e32 v51, v51
	v_rcp_f32_e32 v64, v64
	v_rcp_f32_e32 v65, v65
	v_rcp_f32_e32 v52, v52
	v_cvt_u32_f32_e32 v63, v63
	v_cvt_u32_f32_e32 v62, v62
	v_cvt_u32_f32_e32 v54, v54
	v_cvt_u32_f32_e32 v55, v55
	v_rcp_f32_e32 v56, v56
	v_rcp_f32_e32 v57, v57
	v_lshl_or_b32 v58, v67, 8, v50
	v_lshl_or_b32 v59, v66, 8, v51
	v_pk_fma_f32 v[50:51], v[60:61], s[16:17], 0.5 op_sel_hi:[1,0,0]
; __device__ __forceinline__ float sigmoidf_fast(float x) { return __builtin_amdgcn_rcpf(1.0f + __builtin_amdgcn_exp2f(-1.4426950408889634f * x)); }
;     __device__ __forceinline__ void operator()(const f32x4 (&acc)[2][2][4][2], const Unit& u, int wr, int wc, int fr, int fq) const {
;     ...
;         if (u.pn >= 30) {
;             const int tidn = (wr * 4 + wc) * 64 + fq * 16 + fr;
;             u32x4* gp = (u32x4*)G8 + (size_t)(u.pm * 16 + (u.pn - 30)) * 8 * 512 + tidn;
; #pragma unroll
;             for (int ai = 0; ai < 2; ++ai)
; #pragma unroll
;                 for (int m = 0; m < 4; ++m) { unsigned q[16];
; #pragma unroll
;                     for (int bj = 0; bj < 2; ++bj) { const f32x4 v0 = acc[ai][bj][m][0], v1 = acc[ai][bj][m][1];
; #pragma unroll
;                         for (int e = 0; e < 4; ++e) { q[8 * bj + e] = (unsigned)fmaf(sigmoidf_fast(v0[e]), 255.0f, 0.5f); q[8 * bj + 4 + e] = (unsigned)fmaf(sigmoidf_fast(v1[e]), 255.0f, 0.5f); } }
;                     u32x4 w; w.x = q[0] | (q[1] << 8) | (q[2] << 16) | (q[3] << 24); w.y = q[4] | (q[5] << 8) | (q[6] << 16) | (q[7] << 24);
;                     w.z = q[8] | (q[9] << 8) | (q[10] << 16) | (q[11] << 24); w.w = q[12] | (q[13] << 8) | (q[14] << 16) | (q[15] << 24);
;                     gp[(ai * 4 + m) * 512] = w; }
	v_lshl_or_b32 v54, v62, 8, v54
	v_lshl_or_b32 v55, v63, 8, v55
	v_pk_fma_f32 v[52:53], v[52:53], s[16:17], 0.5 op_sel_hi:[1,0,0]
	v_cvt_u32_f32_sdwa v62, v51 dst_sel:WORD_1 dst_unused:UNUSED_PAD src0_sel:DWORD
	v_cvt_u32_f32_sdwa v63, v50 dst_sel:WORD_1 dst_unused:UNUSED_PAD src0_sel:DWORD
	v_pk_fma_f32 v[50:51], v[64:65], s[16:17], 0.5 op_sel_hi:[1,0,0]
	v_cvt_u32_f32_sdwa v60, v53 dst_sel:WORD_1 dst_unused:UNUSED_PAD src0_sel:DWORD
	v_cvt_u32_f32_sdwa v61, v52 dst_sel:WORD_1 dst_unused:UNUSED_PAD src0_sel:DWORD
	v_pk_fma_f32 v[52:53], v[56:57], s[16:17], 0.5 op_sel_hi:[1,0,0]
	v_cvt_u32_f32_sdwa v50, v50 dst_sel:BYTE_3 dst_unused:UNUSED_PAD src0_sel:DWORD
	v_cvt_u32_f32_sdwa v53, v53 dst_sel:BYTE_3 dst_unused:UNUSED_PAD src0_sel:DWORD
	v_cvt_u32_f32_sdwa v52, v52 dst_sel:BYTE_3 dst_unused:UNUSED_PAD src0_sel:DWORD
	v_cvt_u32_f32_sdwa v51, v51 dst_sel:BYTE_3 dst_unused:UNUSED_PAD src0_sel:DWORD
	s_mov_b32 s7, 0x8000
	v_or3_b32 v50, v54, v63, v50
	v_add_co_u32_e32 v54, vcc, s7, v156
	v_pk_mul_f32 v[46:47], v[46:47], v[204:205] op_sel_hi:[1,0]
	v_pk_mul_f32 v[42:43], v[42:43], v[204:205] op_sel_hi:[1,0]
	v_or3_b32 v53, v59, v60, v53
	v_or3_b32 v52, v58, v61, v52
	v_or3_b32 v51, v55, v62, v51
	v_addc_co_u32_e32 v55, vcc, 0, v157, vcc
	v_exp_f32_e32 v46, v46
	v_exp_f32_e32 v56, v42
	global_store_dwordx4 v[54:55], v[50:53], off
	v_exp_f32_e32 v47, v47
	v_add_f32_e32 v42, 1.0, v46
	v_exp_f32_e32 v50, v43
	v_add_f32_e32 v46, 1.0, v56
	v_pk_mul_f32 v[48:49], v[48:49], v[204:205] op_sel_hi:[1,0]
	v_pk_mul_f32 v[44:45], v[44:45], v[204:205] op_sel_hi:[1,0]
	v_rcp_f32_e32 v43, v46
	v_add_f32_e32 v46, 1.0, v47
	v_add_f32_e32 v47, 1.0, v50
	v_exp_f32_e32 v48, v48
	v_exp_f32_e32 v50, v44
	v_add_f32_e32 v44, 1.0, v48
	v_add_f32_e32 v48, 1.0, v50
	v_exp_f32_e32 v49, v49
	v_exp_f32_e32 v50, v45
	v_pk_mul_f32 v[38:39], v[38:39], v[204:205] op_sel_hi:[1,0]
	v_pk_mul_f32 v[34:35], v[34:35], v[204:205] op_sel_hi:[1,0]
	v_rcp_f32_e32 v45, v48
	v_add_f32_e32 v48, 1.0, v49
	v_add_f32_e32 v49, 1.0, v50
	v_exp_f32_e32 v38, v38
	v_exp_f32_e32 v50, v34
	v_add_f32_e32 v34, 1.0, v38
	v_add_f32_e32 v38, 1.0, v50
	v_exp_f32_e32 v39, v39
	v_exp_f32_e32 v50, v35
	v_pk_mul_f32 v[40:41], v[40:41], v[204:205] op_sel_hi:[1,0]
	v_pk_mul_f32 v[36:37], v[36:37], v[204:205] op_sel_hi:[1,0]
	v_rcp_f32_e32 v35, v38
	v_add_f32_e32 v38, 1.0, v39
	v_add_f32_e32 v39, 1.0, v50
	v_exp_f32_e32 v40, v40
	v_exp_f32_e32 v50, v36
	v_rcp_f32_e32 v34, v34
	v_rcp_f32_e32 v38, v38
	v_rcp_f32_e32 v39, v39
	v_rcp_f32_e32 v42, v42
	v_rcp_f32_e32 v46, v46
	v_rcp_f32_e32 v47, v47
	v_add_f32_e32 v36, 1.0, v40
	v_add_f32_e32 v40, 1.0, v50
	v_exp_f32_e32 v41, v41
	v_exp_f32_e32 v50, v37
	v_pk_fma_f32 v[38:39], v[38:39], s[16:17], 0.5 op_sel_hi:[1,0,0]
	v_pk_fma_f32 v[34:35], v[34:35], s[16:17], 0.5 op_sel_hi:[1,0,0]
	v_rcp_f32_e32 v44, v44
	v_rcp_f32_e32 v37, v40
	v_add_f32_e32 v40, 1.0, v41
	v_add_f32_e32 v41, 1.0, v50
	v_pk_fma_f32 v[46:47], v[46:47], s[16:17], 0.5 op_sel_hi:[1,0,0]
	v_cvt_u32_f32_e32 v50, v39
	v_cvt_u32_f32_e32 v51, v38
	v_pk_fma_f32 v[38:39], v[42:43], s[16:17], 0.5 op_sel_hi:[1,0,0]
	v_cvt_u32_f32_e32 v34, v34
	v_cvt_u32_f32_e32 v35, v35
	v_rcp_f32_e32 v48, v48
	v_rcp_f32_e32 v49, v49
	v_rcp_f32_e32 v36, v36
	v_cvt_u32_f32_e32 v47, v47
	v_cvt_u32_f32_e32 v46, v46
	v_cvt_u32_f32_e32 v38, v38
	v_cvt_u32_f32_e32 v39, v39
	v_rcp_f32_e32 v40, v40
	v_rcp_f32_e32 v41, v41
	v_lshl_or_b32 v42, v51, 8, v34
	v_lshl_or_b32 v43, v50, 8, v35
	v_pk_fma_f32 v[34:35], v[44:45], s[16:17], 0.5 op_sel_hi:[1,0,0]
	v_lshl_or_b32 v38, v46, 8, v38
	v_lshl_or_b32 v39, v47, 8, v39
	v_pk_fma_f32 v[36:37], v[36:37], s[16:17], 0.5 op_sel_hi:[1,0,0]
	v_cvt_u32_f32_sdwa v46, v35 dst_sel:WORD_1 dst_unused:UNUSED_PAD src0_sel:DWORD
	v_cvt_u32_f32_sdwa v47, v34 dst_sel:WORD_1 dst_unused:UNUSED_PAD src0_sel:DWORD
	v_pk_fma_f32 v[34:35], v[48:49], s[16:17], 0.5 op_sel_hi:[1,0,0]
	v_cvt_u32_f32_sdwa v44, v37 dst_sel:WORD_1 dst_unused:UNUSED_PAD src0_sel:DWORD
	v_cvt_u32_f32_sdwa v45, v36 dst_sel:WORD_1 dst_unused:UNUSED_PAD src0_sel:DWORD
	v_pk_fma_f32 v[36:37], v[40:41], s[16:17], 0.5 op_sel_hi:[1,0,0]
	v_cvt_u32_f32_sdwa v34, v34 dst_sel:BYTE_3 dst_unused:UNUSED_PAD src0_sel:DWORD
	v_cvt_u32_f32_sdwa v37, v37 dst_sel:BYTE_3 dst_unused:UNUSED_PAD src0_sel:DWORD
	v_cvt_u32_f32_sdwa v36, v36 dst_sel:BYTE_3 dst_unused:UNUSED_PAD src0_sel:DWORD
	v_cvt_u32_f32_sdwa v35, v35 dst_sel:BYTE_3 dst_unused:UNUSED_PAD src0_sel:DWORD
	s_mov_b32 s7, 0xa000
	v_or3_b32 v34, v38, v47, v34
	v_add_co_u32_e32 v38, vcc, s7, v156
	v_pk_mul_f32 v[30:31], v[30:31], v[204:205] op_sel_hi:[1,0]
	v_pk_mul_f32 v[26:27], v[26:27], v[204:205] op_sel_hi:[1,0]
	v_or3_b32 v37, v43, v44, v37
	v_or3_b32 v36, v42, v45, v36
	v_or3_b32 v35, v39, v46, v35
	v_addc_co_u32_e32 v39, vcc, 0, v157, vcc
	v_exp_f32_e32 v30, v30
	v_exp_f32_e32 v40, v26
	global_store_dwordx4 v[38:39], v[34:37], off
	v_exp_f32_e32 v31, v31
	v_add_f32_e32 v26, 1.0, v30
	v_exp_f32_e32 v34, v27
	v_add_f32_e32 v30, 1.0, v40
	v_pk_mul_f32 v[32:33], v[32:33], v[204:205] op_sel_hi:[1,0]
	v_pk_mul_f32 v[28:29], v[28:29], v[204:205] op_sel_hi:[1,0]
	v_rcp_f32_e32 v27, v30
	v_add_f32_e32 v30, 1.0, v31
	v_add_f32_e32 v31, 1.0, v34
	v_exp_f32_e32 v32, v32
	v_exp_f32_e32 v34, v28
	v_add_f32_e32 v28, 1.0, v32
	v_add_f32_e32 v32, 1.0, v34
	v_exp_f32_e32 v33, v33
	v_exp_f32_e32 v34, v29
	v_pk_mul_f32 v[22:23], v[22:23], v[204:205] op_sel_hi:[1,0]
	v_pk_mul_f32 v[18:19], v[18:19], v[204:205] op_sel_hi:[1,0]
	v_rcp_f32_e32 v29, v32
	v_add_f32_e32 v32, 1.0, v33
	v_add_f32_e32 v33, 1.0, v34
	v_exp_f32_e32 v22, v22
	v_exp_f32_e32 v34, v18
	v_add_f32_e32 v18, 1.0, v22
	v_add_f32_e32 v22, 1.0, v34
; __device__ __forceinline__ float sigmoidf_fast(float x) { return __builtin_amdgcn_rcpf(1.0f + __builtin_amdgcn_exp2f(-1.4426950408889634f * x)); }
;     __device__ __forceinline__ void operator()(const f32x4 (&acc)[2][2][4][2], const Unit& u, int wr, int wc, int fr, int fq) const {
;     ...
;         if (u.pn >= 30) {
;             const int tidn = (wr * 4 + wc) * 64 + fq * 16 + fr;
;             u32x4* gp = (u32x4*)G8 + (size_t)(u.pm * 16 + (u.pn - 30)) * 8 * 512 + tidn;
; #pragma unroll
;             for (int ai = 0; ai < 2; ++ai)
; #pragma unroll
;                 for (int m = 0; m < 4; ++m) { unsigned q[16];
; #pragma unroll
;                     for (int bj = 0; bj < 2; ++bj) { const f32x4 v0 = acc[ai][bj][m][0], v1 = acc[ai][bj][m][1];
; #pragma unroll
;                         for (int e = 0; e < 4; ++e) { q[8 * bj + e] = (unsigned)fmaf(sigmoidf_fast(v0[e]), 255.0f, 0.5f); q[8 * bj + 4 + e] = (unsigned)fmaf(sigmoidf_fast(v1[e]), 255.0f, 0.5f); } }
;                     u32x4 w; w.x = q[0] | (q[1] << 8) | (q[2] << 16) | (q[3] << 24); w.y = q[4] | (q[5] << 8) | (q[6] << 16) | (q[7] << 24);
;                     w.z = q[8] | (q[9] << 8) | (q[10] << 16) | (q[11] << 24); w.w = q[12] | (q[13] << 8) | (q[14] << 16) | (q[15] << 24);
;                     gp[(ai * 4 + m) * 512] = w; }
	v_exp_f32_e32 v23, v23
	v_exp_f32_e32 v34, v19
	v_pk_mul_f32 v[24:25], v[24:25], v[204:205] op_sel_hi:[1,0]
	v_pk_mul_f32 v[20:21], v[20:21], v[204:205] op_sel_hi:[1,0]
	v_rcp_f32_e32 v19, v22
	v_add_f32_e32 v22, 1.0, v23
	v_add_f32_e32 v23, 1.0, v34
	v_exp_f32_e32 v24, v24
	v_exp_f32_e32 v34, v20
	v_rcp_f32_e32 v18, v18
	v_rcp_f32_e32 v22, v22
	v_rcp_f32_e32 v23, v23
	v_rcp_f32_e32 v26, v26
	v_rcp_f32_e32 v30, v30
	v_rcp_f32_e32 v31, v31
	v_add_f32_e32 v20, 1.0, v24
	v_add_f32_e32 v24, 1.0, v34
	v_exp_f32_e32 v25, v25
	v_exp_f32_e32 v34, v21
	v_pk_fma_f32 v[22:23], v[22:23], s[16:17], 0.5 op_sel_hi:[1,0,0]
	v_pk_fma_f32 v[18:19], v[18:19], s[16:17], 0.5 op_sel_hi:[1,0,0]
	v_rcp_f32_e32 v28, v28
	v_rcp_f32_e32 v21, v24
	v_add_f32_e32 v24, 1.0, v25
	v_add_f32_e32 v25, 1.0, v34
	v_pk_fma_f32 v[30:31], v[30:31], s[16:17], 0.5 op_sel_hi:[1,0,0]
	v_cvt_u32_f32_e32 v34, v23
	v_cvt_u32_f32_e32 v35, v22
	v_pk_fma_f32 v[22:23], v[26:27], s[16:17], 0.5 op_sel_hi:[1,0,0]
	v_cvt_u32_f32_e32 v18, v18
	v_cvt_u32_f32_e32 v19, v19
	v_rcp_f32_e32 v32, v32
	v_rcp_f32_e32 v33, v33
	v_rcp_f32_e32 v20, v20
	v_cvt_u32_f32_e32 v31, v31
	v_cvt_u32_f32_e32 v30, v30
	v_cvt_u32_f32_e32 v22, v22
	v_cvt_u32_f32_e32 v23, v23
	v_rcp_f32_e32 v24, v24
	v_rcp_f32_e32 v25, v25
	v_lshl_or_b32 v26, v35, 8, v18
	v_lshl_or_b32 v27, v34, 8, v19
	v_pk_fma_f32 v[18:19], v[28:29], s[16:17], 0.5 op_sel_hi:[1,0,0]
	v_lshl_or_b32 v22, v30, 8, v22
	v_lshl_or_b32 v23, v31, 8, v23
	v_pk_fma_f32 v[20:21], v[20:21], s[16:17], 0.5 op_sel_hi:[1,0,0]
	v_cvt_u32_f32_sdwa v30, v19 dst_sel:WORD_1 dst_unused:UNUSED_PAD src0_sel:DWORD
	v_cvt_u32_f32_sdwa v31, v18 dst_sel:WORD_1 dst_unused:UNUSED_PAD src0_sel:DWORD
	v_pk_fma_f32 v[18:19], v[32:33], s[16:17], 0.5 op_sel_hi:[1,0,0]
	v_cvt_u32_f32_sdwa v28, v21 dst_sel:WORD_1 dst_unused:UNUSED_PAD src0_sel:DWORD
	v_cvt_u32_f32_sdwa v29, v20 dst_sel:WORD_1 dst_unused:UNUSED_PAD src0_sel:DWORD
	v_pk_fma_f32 v[20:21], v[24:25], s[16:17], 0.5 op_sel_hi:[1,0,0]
	v_cvt_u32_f32_sdwa v18, v18 dst_sel:BYTE_3 dst_unused:UNUSED_PAD src0_sel:DWORD
	v_cvt_u32_f32_sdwa v21, v21 dst_sel:BYTE_3 dst_unused:UNUSED_PAD src0_sel:DWORD
	v_cvt_u32_f32_sdwa v20, v20 dst_sel:BYTE_3 dst_unused:UNUSED_PAD src0_sel:DWORD
	v_cvt_u32_f32_sdwa v19, v19 dst_sel:BYTE_3 dst_unused:UNUSED_PAD src0_sel:DWORD
	s_mov_b32 s7, 0xc000
	v_or3_b32 v18, v22, v31, v18
	v_add_co_u32_e32 v22, vcc, s7, v156
	v_pk_mul_f32 v[14:15], v[14:15], v[204:205] op_sel_hi:[1,0]
	v_pk_mul_f32 v[10:11], v[10:11], v[204:205] op_sel_hi:[1,0]
	v_or3_b32 v21, v27, v28, v21
	v_or3_b32 v20, v26, v29, v20
	v_or3_b32 v19, v23, v30, v19
	v_addc_co_u32_e32 v23, vcc, 0, v157, vcc
	v_exp_f32_e32 v14, v14
	v_exp_f32_e32 v24, v10
	global_store_dwordx4 v[22:23], v[18:21], off
	v_exp_f32_e32 v15, v15
	v_add_f32_e32 v10, 1.0, v14
	v_exp_f32_e32 v18, v11
	v_add_f32_e32 v14, 1.0, v24
	v_pk_mul_f32 v[16:17], v[16:17], v[204:205] op_sel_hi:[1,0]
	v_pk_mul_f32 v[12:13], v[12:13], v[204:205] op_sel_hi:[1,0]
	v_rcp_f32_e32 v11, v14
	v_add_f32_e32 v14, 1.0, v15
	v_add_f32_e32 v15, 1.0, v18
	v_exp_f32_e32 v16, v16
	v_exp_f32_e32 v18, v12
	v_add_f32_e32 v12, 1.0, v16
	v_add_f32_e32 v16, 1.0, v18
	v_exp_f32_e32 v17, v17
	v_exp_f32_e32 v18, v13
	v_pk_mul_f32 v[6:7], v[6:7], v[204:205] op_sel_hi:[1,0]
	v_pk_mul_f32 v[2:3], v[2:3], v[204:205] op_sel_hi:[1,0]
	v_rcp_f32_e32 v13, v16
	v_add_f32_e32 v16, 1.0, v17
	v_add_f32_e32 v17, 1.0, v18
	v_exp_f32_e32 v6, v6
	v_exp_f32_e32 v18, v2
	v_add_f32_e32 v2, 1.0, v6
	v_add_f32_e32 v6, 1.0, v18
	v_exp_f32_e32 v7, v7
	v_exp_f32_e32 v18, v3
	v_pk_mul_f32 v[8:9], v[8:9], v[204:205] op_sel_hi:[1,0]
	v_pk_mul_f32 v[4:5], v[4:5], v[204:205] op_sel_hi:[1,0]
	v_rcp_f32_e32 v3, v6
	v_add_f32_e32 v6, 1.0, v7
	v_add_f32_e32 v7, 1.0, v18
	v_exp_f32_e32 v8, v8
	v_exp_f32_e32 v18, v4
	v_rcp_f32_e32 v2, v2
	v_rcp_f32_e32 v6, v6
	v_rcp_f32_e32 v7, v7
	v_rcp_f32_e32 v10, v10
	v_rcp_f32_e32 v14, v14
	v_rcp_f32_e32 v15, v15
	v_add_f32_e32 v4, 1.0, v8
	v_add_f32_e32 v8, 1.0, v18
	v_exp_f32_e32 v9, v9
	v_exp_f32_e32 v18, v5
	v_pk_fma_f32 v[6:7], v[6:7], s[16:17], 0.5 op_sel_hi:[1,0,0]
	v_pk_fma_f32 v[2:3], v[2:3], s[16:17], 0.5 op_sel_hi:[1,0,0]
	v_rcp_f32_e32 v12, v12
	v_rcp_f32_e32 v5, v8
	v_add_f32_e32 v8, 1.0, v9
	v_add_f32_e32 v9, 1.0, v18
	v_pk_fma_f32 v[14:15], v[14:15], s[16:17], 0.5 op_sel_hi:[1,0,0]
	v_cvt_u32_f32_e32 v18, v7
	v_cvt_u32_f32_e32 v19, v6
	v_pk_fma_f32 v[6:7], v[10:11], s[16:17], 0.5 op_sel_hi:[1,0,0]
	v_cvt_u32_f32_e32 v2, v2
	v_cvt_u32_f32_e32 v3, v3
	v_rcp_f32_e32 v16, v16
	v_rcp_f32_e32 v17, v17
	v_rcp_f32_e32 v4, v4
	v_cvt_u32_f32_e32 v15, v15
	v_cvt_u32_f32_e32 v14, v14
	v_cvt_u32_f32_e32 v6, v6
	v_cvt_u32_f32_e32 v7, v7
	v_rcp_f32_e32 v8, v8
	v_rcp_f32_e32 v9, v9
	v_lshl_or_b32 v10, v19, 8, v2
	v_lshl_or_b32 v11, v18, 8, v3
	v_pk_fma_f32 v[2:3], v[12:13], s[16:17], 0.5 op_sel_hi:[1,0,0]
	v_lshl_or_b32 v6, v14, 8, v6
	v_lshl_or_b32 v7, v15, 8, v7
	v_pk_fma_f32 v[4:5], v[4:5], s[16:17], 0.5 op_sel_hi:[1,0,0]
	v_cvt_u32_f32_sdwa v14, v3 dst_sel:WORD_1 dst_unused:UNUSED_PAD src0_sel:DWORD
	v_cvt_u32_f32_sdwa v15, v2 dst_sel:WORD_1 dst_unused:UNUSED_PAD src0_sel:DWORD
	v_pk_fma_f32 v[2:3], v[16:17], s[16:17], 0.5 op_sel_hi:[1,0,0]
	v_cvt_u32_f32_sdwa v12, v5 dst_sel:WORD_1 dst_unused:UNUSED_PAD src0_sel:DWORD
	v_cvt_u32_f32_sdwa v13, v4 dst_sel:WORD_1 dst_unused:UNUSED_PAD src0_sel:DWORD
	v_pk_fma_f32 v[4:5], v[8:9], s[16:17], 0.5 op_sel_hi:[1,0,0]
	v_cvt_u32_f32_sdwa v2, v2 dst_sel:BYTE_3 dst_unused:UNUSED_PAD src0_sel:DWORD
	v_cvt_u32_f32_sdwa v5, v5 dst_sel:BYTE_3 dst_unused:UNUSED_PAD src0_sel:DWORD
	v_cvt_u32_f32_sdwa v4, v4 dst_sel:BYTE_3 dst_unused:UNUSED_PAD src0_sel:DWORD
	v_cvt_u32_f32_sdwa v3, v3 dst_sel:BYTE_3 dst_unused:UNUSED_PAD src0_sel:DWORD
	v_or3_b32 v2, v6, v15, v2
	v_add_co_u32_e32 v6, vcc, 0xe000, v156
	v_or3_b32 v5, v11, v12, v5
	v_or3_b32 v4, v10, v13, v4
	v_or3_b32 v3, v7, v14, v3
	v_addc_co_u32_e32 v7, vcc, 0, v157, vcc
	global_store_dwordx4 v[6:7], v[2:5], off
	s_andn2_b64 vcc, exec, s[40:41]
	s_mov_b64 s[18:19], -1
	s_cbranch_vccnz .LBB0_277
